# speedup vs baseline: 1.0085x; 1.0016x over previous
.LBB0_27:
	s_add_u32 s58, s24, 0xfffc0080
	s_addc_u32 s59, s25, -1
	s_add_i32 s80, 0, 0x10000
	s_cmp_eq_u32 s84, 12
	s_cselect_b32 s61, s18, s59
	s_cselect_b32 s60, s19, s58
	v_add_u32_e32 v128, s80, v209
	s_cselect_b32 s59, s13, s77
	s_cselect_b32 s58, s53, s76
	s_add_i32 s81, 0, 0x14000
	ds_read_b128 v[130:133], v128
	ds_read_b128 v[134:137], v128 offset:1024
	ds_read_b128 v[138:141], v128 offset:2048
	ds_read_b128 v[142:145], v128 offset:3072
	v_add_u32_e32 v128, s81, v209
	ds_read_b128 v[146:149], v128
	ds_read_b128 v[150:153], v128 offset:1024
	ds_read_b128 v[154:157], v128 offset:2048
	ds_read_b128 v[158:161], v128 offset:3072
	s_add_i32 m0, s16, 0xc000
	ds_read_b128 v[162:165], v211
	ds_read_b128 v[166:169], v211 offset:1024
	ds_read_b128 v[170:173], v211 offset:2048
	ds_read_b128 v[174:177], v211 offset:3072
	ds_read_b128 v[178:181], v211 offset:4096
	ds_read_b128 v[182:185], v211 offset:5120
	ds_read_b128 v[212:215], v211 offset:6144
	ds_read_b128 v[216:219], v211 offset:7168
	global_load_lds_dwordx4 v202, s[24:25]
	s_add_i32 m0, s16, 0xe000
	s_nop 0
	global_load_lds_dwordx4 v204, s[24:25]
	s_waitcnt vmcnt(8)
	s_waitcnt lgkmcnt(0)
	s_barrier
	s_setprio 1
	s_waitcnt lgkmcnt(0)
	v_mfma_f32_16x16x32_bf16 v[124:127], v[130:133], v[162:165], v[124:127]
	v_mfma_f32_16x16x32_bf16 v[120:123], v[138:141], v[162:165], v[120:123]
	v_mfma_f32_16x16x32_bf16 v[116:119], v[130:133], v[170:173], v[116:119]
	v_mfma_f32_16x16x32_bf16 v[112:115], v[138:141], v[170:173], v[112:115]
	v_mfma_f32_16x16x32_bf16 v[108:111], v[130:133], v[178:181], v[108:111]
	v_mfma_f32_16x16x32_bf16 v[104:107], v[138:141], v[178:181], v[104:107]
	v_mfma_f32_16x16x32_bf16 v[100:103], v[130:133], v[212:215], v[100:103]
	v_mfma_f32_16x16x32_bf16 v[96:99], v[138:141], v[212:215], v[96:99]
	v_mfma_f32_16x16x32_bf16 v[124:127], v[134:137], v[166:169], v[124:127]
	v_mfma_f32_16x16x32_bf16 v[120:123], v[142:145], v[166:169], v[120:123]
	v_mfma_f32_16x16x32_bf16 v[116:119], v[134:137], v[174:177], v[116:119]
	v_mfma_f32_16x16x32_bf16 v[112:115], v[142:145], v[174:177], v[112:115]
	v_mfma_f32_16x16x32_bf16 v[108:111], v[134:137], v[182:185], v[108:111]
	v_mfma_f32_16x16x32_bf16 v[104:107], v[142:145], v[182:185], v[104:107]
	v_mfma_f32_16x16x32_bf16 v[100:103], v[134:137], v[216:219], v[100:103]
	v_mfma_f32_16x16x32_bf16 v[96:99], v[142:145], v[216:219], v[96:99]
	s_setprio 0
	s_setprio 1
	v_mfma_f32_16x16x32_bf16 v[92:95], v[146:149], v[162:165], v[92:95]
	v_mfma_f32_16x16x32_bf16 v[88:91], v[154:157], v[162:165], v[88:91]
	v_mfma_f32_16x16x32_bf16 v[84:87], v[146:149], v[170:173], v[84:87]
	v_mfma_f32_16x16x32_bf16 v[80:83], v[154:157], v[170:173], v[80:83]
	v_mfma_f32_16x16x32_bf16 v[76:79], v[146:149], v[178:181], v[76:79]
	v_mfma_f32_16x16x32_bf16 v[72:75], v[154:157], v[178:181], v[72:75]
	v_mfma_f32_16x16x32_bf16 v[68:71], v[146:149], v[212:215], v[68:71]
	v_mfma_f32_16x16x32_bf16 v[64:67], v[154:157], v[212:215], v[64:67]
	v_mfma_f32_16x16x32_bf16 v[92:95], v[150:153], v[166:169], v[92:95]
	v_mfma_f32_16x16x32_bf16 v[88:91], v[158:161], v[166:169], v[88:91]
	v_mfma_f32_16x16x32_bf16 v[84:87], v[150:153], v[174:177], v[84:87]
	v_mfma_f32_16x16x32_bf16 v[80:83], v[158:161], v[174:177], v[80:83]
	v_mfma_f32_16x16x32_bf16 v[76:79], v[150:153], v[182:185], v[76:79]
	v_mfma_f32_16x16x32_bf16 v[72:75], v[158:161], v[182:185], v[72:75]
	v_mfma_f32_16x16x32_bf16 v[68:71], v[150:153], v[216:219], v[68:71]
	v_mfma_f32_16x16x32_bf16 v[64:67], v[158:161], v[216:219], v[64:67]
	s_setprio 0
	s_barrier
	s_add_i32 s80, s80, s33
	v_lshl_add_u64 v[186:187], s[58:59], 0, v[196:197]
	s_mov_b32 m0, s80
	ds_read_b128 v[162:165], v211 offset:16384
	ds_read_b128 v[166:169], v211 offset:17408
	ds_read_b128 v[170:173], v211 offset:18432
	ds_read_b128 v[174:177], v211 offset:19456
	ds_read_b128 v[178:181], v211 offset:20480
	ds_read_b128 v[182:185], v211 offset:21504
	ds_read_b128 v[212:215], v211 offset:22528
	ds_read_b128 v[216:219], v211 offset:23552
	global_load_lds_dwordx4 v[186:187], off
	s_add_i32 m0, s80, 0x2000
	s_add_u32 s96, s58, 0x40000
	v_lshl_add_u64 v[190:191], s[58:59], 0, v[192:193]
	s_addc_u32 s97, s59, 0
	s_add_i32 s80, s81, s33
	global_load_lds_dwordx4 v[190:191], off
	s_mov_b32 m0, s80
	v_lshl_add_u64 v[220:221], s[60:61], 0, v[194:195]
	global_load_lds_dwordx4 v196, s[96:97]
	s_add_i32 m0, s80, 0x2000
	s_nop 0
	global_load_lds_dwordx4 v192, s[96:97]
	v_lshl_add_u64 v[206:207], s[60:61], 0, v[198:199]
	s_mov_b32 m0, s16
	s_nop 0
	global_load_lds_dwordx4 v[206:207], off
	s_mov_b32 m0, s17
	s_nop 0
	global_load_lds_dwordx4 v[220:221], off
	s_waitcnt vmcnt(8)
	s_waitcnt lgkmcnt(0)
	s_barrier
	s_setprio 1
	s_waitcnt lgkmcnt(0)
	v_mfma_f32_16x16x32_bf16 v[60:63], v[130:133], v[162:165], v[60:63]
	v_mfma_f32_16x16x32_bf16 v[56:59], v[138:141], v[162:165], v[56:59]
	v_mfma_f32_16x16x32_bf16 v[52:55], v[130:133], v[170:173], v[52:55]
	v_mfma_f32_16x16x32_bf16 v[48:51], v[138:141], v[170:173], v[48:51]
	v_mfma_f32_16x16x32_bf16 v[44:47], v[130:133], v[178:181], v[44:47]
	v_mfma_f32_16x16x32_bf16 v[40:43], v[138:141], v[178:181], v[40:43]
	v_mfma_f32_16x16x32_bf16 v[36:39], v[130:133], v[212:215], v[36:39]
	v_mfma_f32_16x16x32_bf16 v[32:35], v[138:141], v[212:215], v[32:35]
	v_mfma_f32_16x16x32_bf16 v[60:63], v[134:137], v[166:169], v[60:63]
	v_mfma_f32_16x16x32_bf16 v[56:59], v[142:145], v[166:169], v[56:59]
	v_mfma_f32_16x16x32_bf16 v[52:55], v[134:137], v[174:177], v[52:55]
	v_mfma_f32_16x16x32_bf16 v[48:51], v[142:145], v[174:177], v[48:51]
	v_mfma_f32_16x16x32_bf16 v[44:47], v[134:137], v[182:185], v[44:47]
	v_mfma_f32_16x16x32_bf16 v[40:43], v[142:145], v[182:185], v[40:43]
	v_mfma_f32_16x16x32_bf16 v[36:39], v[134:137], v[216:219], v[36:39]
	v_mfma_f32_16x16x32_bf16 v[32:35], v[142:145], v[216:219], v[32:35]
	s_setprio 0
	s_setprio 1
	v_mfma_f32_16x16x32_bf16 v[28:31], v[146:149], v[162:165], v[28:31]
	v_mfma_f32_16x16x32_bf16 v[24:27], v[154:157], v[162:165], v[24:27]
	v_mfma_f32_16x16x32_bf16 v[20:23], v[146:149], v[170:173], v[20:23]
	v_mfma_f32_16x16x32_bf16 v[16:19], v[154:157], v[170:173], v[16:19]
	v_mfma_f32_16x16x32_bf16 v[12:15], v[146:149], v[178:181], v[12:15]
	v_mfma_f32_16x16x32_bf16 v[8:11], v[154:157], v[178:181], v[8:11]
	v_mfma_f32_16x16x32_bf16 v[4:7], v[146:149], v[212:215], v[4:7]
	v_mfma_f32_16x16x32_bf16 v[0:3], v[154:157], v[212:215], v[0:3]
	v_mfma_f32_16x16x32_bf16 v[28:31], v[150:153], v[166:169], v[28:31]
	v_mfma_f32_16x16x32_bf16 v[24:27], v[158:161], v[166:169], v[24:27]
	v_mfma_f32_16x16x32_bf16 v[20:23], v[150:153], v[174:177], v[20:23]
	v_mfma_f32_16x16x32_bf16 v[16:19], v[158:161], v[174:177], v[16:19]
	v_mfma_f32_16x16x32_bf16 v[12:15], v[150:153], v[182:185], v[12:15]
	v_mfma_f32_16x16x32_bf16 v[8:11], v[158:161], v[182:185], v[8:11]
	v_mfma_f32_16x16x32_bf16 v[4:7], v[150:153], v[216:219], v[4:7]
	v_mfma_f32_16x16x32_bf16 v[0:3], v[158:161], v[216:219], v[0:3]
	s_setprio 0
	s_barrier
	s_add_i32 s80, 0, 0x18000
	v_add_u32_e32 v128, s80, v209
	s_add_i32 s81, 0, 0x1c000
	ds_read_b128 v[130:133], v128
	ds_read_b128 v[134:137], v128 offset:1024
	ds_read_b128 v[138:141], v128 offset:2048
	ds_read_b128 v[142:145], v128 offset:3072
	v_add_u32_e32 v128, s81, v209
	ds_read_b128 v[146:149], v128
	ds_read_b128 v[150:153], v128 offset:1024
	ds_read_b128 v[154:157], v128 offset:2048
	ds_read_b128 v[158:161], v128 offset:3072
	s_add_u32 s60, s60, 0x40000
	s_addc_u32 s61, s61, 0
	s_mov_b32 m0, s23
	ds_read_b128 v[162:165], v211 offset:32768
	ds_read_b128 v[166:169], v211 offset:33792
	ds_read_b128 v[170:173], v211 offset:34816
	ds_read_b128 v[174:177], v211 offset:35840
	ds_read_b128 v[178:181], v211 offset:36864
	ds_read_b128 v[182:185], v211 offset:37888
	ds_read_b128 v[212:215], v211 offset:38912
	ds_read_b128 v[216:219], v211 offset:39936
	global_load_lds_dwordx4 v198, s[60:61]
	s_mov_b32 m0, s44
	s_nop 0
	global_load_lds_dwordx4 v194, s[60:61]
	s_waitcnt vmcnt(8)
	s_waitcnt lgkmcnt(0)
	s_barrier
	s_setprio 1
	s_waitcnt lgkmcnt(0)
	v_mfma_f32_16x16x32_bf16 v[124:127], v[130:133], v[162:165], v[124:127]
	v_mfma_f32_16x16x32_bf16 v[120:123], v[138:141], v[162:165], v[120:123]
	v_mfma_f32_16x16x32_bf16 v[116:119], v[130:133], v[170:173], v[116:119]
	v_mfma_f32_16x16x32_bf16 v[112:115], v[138:141], v[170:173], v[112:115]
	v_mfma_f32_16x16x32_bf16 v[108:111], v[130:133], v[178:181], v[108:111]
	v_mfma_f32_16x16x32_bf16 v[104:107], v[138:141], v[178:181], v[104:107]
	v_mfma_f32_16x16x32_bf16 v[100:103], v[130:133], v[212:215], v[100:103]
	v_mfma_f32_16x16x32_bf16 v[96:99], v[138:141], v[212:215], v[96:99]
	v_mfma_f32_16x16x32_bf16 v[124:127], v[134:137], v[166:169], v[124:127]
	v_mfma_f32_16x16x32_bf16 v[120:123], v[142:145], v[166:169], v[120:123]
	v_mfma_f32_16x16x32_bf16 v[116:119], v[134:137], v[174:177], v[116:119]
	v_mfma_f32_16x16x32_bf16 v[112:115], v[142:145], v[174:177], v[112:115]
	v_mfma_f32_16x16x32_bf16 v[108:111], v[134:137], v[182:185], v[108:111]
	v_mfma_f32_16x16x32_bf16 v[104:107], v[142:145], v[182:185], v[104:107]
	v_mfma_f32_16x16x32_bf16 v[100:103], v[134:137], v[216:219], v[100:103]
	v_mfma_f32_16x16x32_bf16 v[96:99], v[142:145], v[216:219], v[96:99]
	s_setprio 0
	s_setprio 1
	v_mfma_f32_16x16x32_bf16 v[92:95], v[146:149], v[162:165], v[92:95]
	v_mfma_f32_16x16x32_bf16 v[88:91], v[154:157], v[162:165], v[88:91]
	v_mfma_f32_16x16x32_bf16 v[84:87], v[146:149], v[170:173], v[84:87]
	v_mfma_f32_16x16x32_bf16 v[80:83], v[154:157], v[170:173], v[80:83]
	v_mfma_f32_16x16x32_bf16 v[76:79], v[146:149], v[178:181], v[76:79]
	v_mfma_f32_16x16x32_bf16 v[72:75], v[154:157], v[178:181], v[72:75]
	v_mfma_f32_16x16x32_bf16 v[68:71], v[146:149], v[212:215], v[68:71]
	v_mfma_f32_16x16x32_bf16 v[64:67], v[154:157], v[212:215], v[64:67]
	v_mfma_f32_16x16x32_bf16 v[92:95], v[150:153], v[166:169], v[92:95]
	v_mfma_f32_16x16x32_bf16 v[88:91], v[158:161], v[166:169], v[88:91]
	v_mfma_f32_16x16x32_bf16 v[84:87], v[150:153], v[174:177], v[84:87]
	v_mfma_f32_16x16x32_bf16 v[80:83], v[158:161], v[174:177], v[80:83]
	v_mfma_f32_16x16x32_bf16 v[76:79], v[150:153], v[182:185], v[76:79]
	v_mfma_f32_16x16x32_bf16 v[72:75], v[158:161], v[182:185], v[72:75]
	v_mfma_f32_16x16x32_bf16 v[68:71], v[150:153], v[216:219], v[68:71]
	v_mfma_f32_16x16x32_bf16 v[64:67], v[158:161], v[216:219], v[64:67]
	s_setprio 0
	s_barrier
	s_add_i32 s60, s80, s33
	v_lshl_add_u64 v[186:187], v[186:187], 0, s[92:93]
	s_mov_b32 m0, s60
	ds_read_b128 v[162:165], v211 offset:49152
	ds_read_b128 v[166:169], v211 offset:50176
	ds_read_b128 v[170:173], v211 offset:51200
	ds_read_b128 v[174:177], v211 offset:52224
	ds_read_b128 v[178:181], v211 offset:53248
	ds_read_b128 v[182:185], v211 offset:54272
	ds_read_b128 v[212:215], v211 offset:55296
	ds_read_b128 v[216:219], v211 offset:56320
	global_load_lds_dwordx4 v[186:187], off
	s_add_i32 m0, s60, 0x2000
	s_add_u32 s58, s58, 0x40080
	v_lshl_add_u64 v[186:187], v[190:191], 0, s[92:93]
	s_addc_u32 s59, s59, 0
	s_add_i32 s60, s81, s33
	global_load_lds_dwordx4 v[186:187], off
	s_mov_b32 m0, s60
	s_nop 0
	global_load_lds_dwordx4 v196, s[58:59]
	s_add_i32 m0, s60, 0x2000
	s_nop 0
	global_load_lds_dwordx4 v192, s[58:59]
	v_lshl_add_u64 v[186:187], v[206:207], 0, s[92:93]
	s_mov_b32 m0, s63
	s_nop 0
	global_load_lds_dwordx4 v[186:187], off
	v_lshl_add_u64 v[186:187], v[220:221], 0, s[92:93]
	s_mov_b32 m0, s64
	s_nop 0
	global_load_lds_dwordx4 v[186:187], off
	s_waitcnt vmcnt(8)
	s_waitcnt lgkmcnt(0)
	s_barrier
	s_setprio 1
	s_waitcnt lgkmcnt(0)
	v_mfma_f32_16x16x32_bf16 v[60:63], v[130:133], v[162:165], v[60:63]
	v_mfma_f32_16x16x32_bf16 v[56:59], v[138:141], v[162:165], v[56:59]
	v_mfma_f32_16x16x32_bf16 v[52:55], v[130:133], v[170:173], v[52:55]
	v_mfma_f32_16x16x32_bf16 v[48:51], v[138:141], v[170:173], v[48:51]
	v_mfma_f32_16x16x32_bf16 v[44:47], v[130:133], v[178:181], v[44:47]
	v_mfma_f32_16x16x32_bf16 v[40:43], v[138:141], v[178:181], v[40:43]
	v_mfma_f32_16x16x32_bf16 v[36:39], v[130:133], v[212:215], v[36:39]
	v_mfma_f32_16x16x32_bf16 v[32:35], v[138:141], v[212:215], v[32:35]
	v_mfma_f32_16x16x32_bf16 v[60:63], v[134:137], v[166:169], v[60:63]
	v_mfma_f32_16x16x32_bf16 v[56:59], v[142:145], v[166:169], v[56:59]
	v_mfma_f32_16x16x32_bf16 v[52:55], v[134:137], v[174:177], v[52:55]
	v_mfma_f32_16x16x32_bf16 v[48:51], v[142:145], v[174:177], v[48:51]
	v_mfma_f32_16x16x32_bf16 v[44:47], v[134:137], v[182:185], v[44:47]
	v_mfma_f32_16x16x32_bf16 v[40:43], v[142:145], v[182:185], v[40:43]
	v_mfma_f32_16x16x32_bf16 v[36:39], v[134:137], v[216:219], v[36:39]
	v_mfma_f32_16x16x32_bf16 v[32:35], v[142:145], v[216:219], v[32:35]
	s_setprio 0
	s_setprio 1
	v_mfma_f32_16x16x32_bf16 v[28:31], v[146:149], v[162:165], v[28:31]
	v_mfma_f32_16x16x32_bf16 v[24:27], v[154:157], v[162:165], v[24:27]
	v_mfma_f32_16x16x32_bf16 v[20:23], v[146:149], v[170:173], v[20:23]
	v_mfma_f32_16x16x32_bf16 v[16:19], v[154:157], v[170:173], v[16:19]
	v_mfma_f32_16x16x32_bf16 v[12:15], v[146:149], v[178:181], v[12:15]
	v_mfma_f32_16x16x32_bf16 v[8:11], v[154:157], v[178:181], v[8:11]
	v_mfma_f32_16x16x32_bf16 v[4:7], v[146:149], v[212:215], v[4:7]
	v_mfma_f32_16x16x32_bf16 v[0:3], v[154:157], v[212:215], v[0:3]
	v_mfma_f32_16x16x32_bf16 v[28:31], v[150:153], v[166:169], v[28:31]
	v_mfma_f32_16x16x32_bf16 v[24:27], v[158:161], v[166:169], v[24:27]
	v_mfma_f32_16x16x32_bf16 v[20:23], v[150:153], v[174:177], v[20:23]
	v_mfma_f32_16x16x32_bf16 v[16:19], v[158:161], v[174:177], v[16:19]
	v_mfma_f32_16x16x32_bf16 v[12:15], v[150:153], v[182:185], v[12:15]
	v_mfma_f32_16x16x32_bf16 v[8:11], v[158:161], v[182:185], v[8:11]
	v_mfma_f32_16x16x32_bf16 v[4:7], v[150:153], v[216:219], v[4:7]
	v_mfma_f32_16x16x32_bf16 v[0:3], v[158:161], v[216:219], v[0:3]
	s_setprio 0
	s_barrier
	s_add_i32 s84, s84, 2
	s_add_u32 s24, s24, 0x100
	s_addc_u32 s25, s25, 0
	s_add_u32 s76, s76, 0x100
	s_addc_u32 s77, s77, 0
	s_cmp_gt_u32 s84, 13
	s_cbranch_scc0 .LBB0_27
	s_and_b64 vcc, exec, s[10:11]
	s_cbranch_vccz .LBB0_30
	s_barrier

.LBB0_114:
	s_add_u32 s20, s0, 0xfff80080
	s_addc_u32 s66, s1, -1
	s_add_i32 s80, 0, 0x10000
	s_cmp_eq_u32 s90, 28
	s_cselect_b32 s97, s3, s66
	s_cselect_b32 s96, s13, s20
	v_add_u32_e32 v128, s80, v174
	s_cselect_b32 s67, s18, s61
	s_cselect_b32 s66, s19, s59
	s_add_i32 s20, 0, 0x14000
	ds_read_b128 v[130:133], v128
	ds_read_b128 v[134:137], v128 offset:1024
	ds_read_b128 v[152:155], v128 offset:2048
	ds_read_b128 v[156:159], v128 offset:3072
	v_add_u32_e32 v128, s20, v174
	ds_read_b128 v[160:163], v128
	ds_read_b128 v[164:167], v128 offset:1024
	ds_read_b128 v[168:171], v128 offset:2048
	ds_read_b128 v[178:181], v128 offset:3072
	s_add_i32 m0, s25, 0xc000
	ds_read_b128 v[182:185], v176
	ds_read_b128 v[192:195], v176 offset:1024
	ds_read_b128 v[196:199], v176 offset:2048
	ds_read_b128 v[200:203], v176 offset:3072
	ds_read_b128 v[204:207], v176 offset:4096
	ds_read_b128 v[208:211], v176 offset:5120
	ds_read_b128 v[212:215], v176 offset:6144
	ds_read_b128 v[216:219], v176 offset:7168
	global_load_lds_dwordx4 v148, s[0:1]
	s_add_i32 m0, s25, 0xe000
	s_nop 0
	global_load_lds_dwordx4 v150, s[0:1]
	s_waitcnt vmcnt(8)
	s_waitcnt lgkmcnt(0)
	s_barrier
	s_setprio 1
	s_waitcnt lgkmcnt(0)
	v_mfma_f32_16x16x32_bf16 v[124:127], v[130:133], v[182:185], v[124:127]
	v_mfma_f32_16x16x32_bf16 v[120:123], v[152:155], v[182:185], v[120:123]
	v_mfma_f32_16x16x32_bf16 v[108:111], v[130:133], v[196:199], v[108:111]
	v_mfma_f32_16x16x32_bf16 v[104:107], v[152:155], v[196:199], v[104:107]
	v_mfma_f32_16x16x32_bf16 v[92:95], v[130:133], v[204:207], v[92:95]
	v_mfma_f32_16x16x32_bf16 v[88:91], v[152:155], v[204:207], v[88:91]
	v_mfma_f32_16x16x32_bf16 v[76:79], v[130:133], v[212:215], v[76:79]
	v_mfma_f32_16x16x32_bf16 v[72:75], v[152:155], v[212:215], v[72:75]
	v_mfma_f32_16x16x32_bf16 v[124:127], v[134:137], v[192:195], v[124:127]
	v_mfma_f32_16x16x32_bf16 v[120:123], v[156:159], v[192:195], v[120:123]
	v_mfma_f32_16x16x32_bf16 v[108:111], v[134:137], v[200:203], v[108:111]
	v_mfma_f32_16x16x32_bf16 v[104:107], v[156:159], v[200:203], v[104:107]
	v_mfma_f32_16x16x32_bf16 v[92:95], v[134:137], v[208:211], v[92:95]
	v_mfma_f32_16x16x32_bf16 v[88:91], v[156:159], v[208:211], v[88:91]
	v_mfma_f32_16x16x32_bf16 v[76:79], v[134:137], v[216:219], v[76:79]
	v_mfma_f32_16x16x32_bf16 v[72:75], v[156:159], v[216:219], v[72:75]
	s_setprio 0
	s_setprio 1
	v_mfma_f32_16x16x32_bf16 v[116:119], v[160:163], v[182:185], v[116:119]
	v_mfma_f32_16x16x32_bf16 v[112:115], v[168:171], v[182:185], v[112:115]
	v_mfma_f32_16x16x32_bf16 v[100:103], v[160:163], v[196:199], v[100:103]
	v_mfma_f32_16x16x32_bf16 v[96:99], v[168:171], v[196:199], v[96:99]
	v_mfma_f32_16x16x32_bf16 v[84:87], v[160:163], v[204:207], v[84:87]
	v_mfma_f32_16x16x32_bf16 v[80:83], v[168:171], v[204:207], v[80:83]
	v_mfma_f32_16x16x32_bf16 v[68:71], v[160:163], v[212:215], v[68:71]
	v_mfma_f32_16x16x32_bf16 v[64:67], v[168:171], v[212:215], v[64:67]
	v_mfma_f32_16x16x32_bf16 v[116:119], v[164:167], v[192:195], v[116:119]
	v_mfma_f32_16x16x32_bf16 v[112:115], v[178:181], v[192:195], v[112:115]
	v_mfma_f32_16x16x32_bf16 v[100:103], v[164:167], v[200:203], v[100:103]
	v_mfma_f32_16x16x32_bf16 v[96:99], v[178:181], v[200:203], v[96:99]
	v_mfma_f32_16x16x32_bf16 v[84:87], v[164:167], v[208:211], v[84:87]
	v_mfma_f32_16x16x32_bf16 v[80:83], v[178:181], v[208:211], v[80:83]
	v_mfma_f32_16x16x32_bf16 v[68:71], v[164:167], v[216:219], v[68:71]
	v_mfma_f32_16x16x32_bf16 v[64:67], v[178:181], v[216:219], v[64:67]
	s_setprio 0
	s_barrier
	s_add_i32 s80, s80, s33
	v_lshl_add_u64 v[220:221], s[66:67], 0, v[140:141]
	s_mov_b32 m0, s80
	ds_read_b128 v[182:185], v176 offset:16384
	ds_read_b128 v[192:195], v176 offset:17408
	ds_read_b128 v[196:199], v176 offset:18432
	ds_read_b128 v[200:203], v176 offset:19456
	ds_read_b128 v[204:207], v176 offset:20480
	ds_read_b128 v[208:211], v176 offset:21504
	ds_read_b128 v[212:215], v176 offset:22528
	ds_read_b128 v[216:219], v176 offset:23552
	global_load_lds_dwordx4 v[220:221], off
	s_add_i32 m0, s80, 0x2000
	s_add_u32 vcc_lo, s66, 0x80000
	v_lshl_add_u64 v[222:223], s[66:67], 0, v[144:145]
	s_addc_u32 vcc_hi, s67, 0
	s_add_i32 s20, s20, s33
	global_load_lds_dwordx4 v[222:223], off
	v_lshl_add_u64 v[224:225], vcc, 0, v[140:141]
	s_mov_b32 m0, s20
	v_lshl_add_u64 v[226:227], s[96:97], 0, v[142:143]
	global_load_lds_dwordx4 v[224:225], off
	v_lshl_add_u64 v[224:225], vcc, 0, v[144:145]
	s_add_i32 m0, s20, 0x2000
	s_nop 0
	global_load_lds_dwordx4 v[224:225], off
	v_lshl_add_u64 v[224:225], s[96:97], 0, v[138:139]
	s_mov_b32 m0, s25
	s_nop 0
	global_load_lds_dwordx4 v[224:225], off
	s_mov_b32 m0, s21
	s_nop 0
	global_load_lds_dwordx4 v[226:227], off
	s_waitcnt vmcnt(8)
	s_waitcnt lgkmcnt(0)
	s_barrier
	s_setprio 1
	s_waitcnt lgkmcnt(0)
	v_mfma_f32_16x16x32_bf16 v[60:63], v[130:133], v[182:185], v[60:63]
	v_mfma_f32_16x16x32_bf16 v[56:59], v[152:155], v[182:185], v[56:59]
	v_mfma_f32_16x16x32_bf16 v[44:47], v[130:133], v[196:199], v[44:47]
	v_mfma_f32_16x16x32_bf16 v[40:43], v[152:155], v[196:199], v[40:43]
	v_mfma_f32_16x16x32_bf16 v[28:31], v[130:133], v[204:207], v[28:31]
	v_mfma_f32_16x16x32_bf16 v[24:27], v[152:155], v[204:207], v[24:27]
	v_mfma_f32_16x16x32_bf16 v[12:15], v[130:133], v[212:215], v[12:15]
	v_mfma_f32_16x16x32_bf16 v[8:11], v[152:155], v[212:215], v[8:11]
	v_mfma_f32_16x16x32_bf16 v[60:63], v[134:137], v[192:195], v[60:63]
	v_mfma_f32_16x16x32_bf16 v[56:59], v[156:159], v[192:195], v[56:59]
	v_mfma_f32_16x16x32_bf16 v[44:47], v[134:137], v[200:203], v[44:47]
	v_mfma_f32_16x16x32_bf16 v[40:43], v[156:159], v[200:203], v[40:43]
	v_mfma_f32_16x16x32_bf16 v[28:31], v[134:137], v[208:211], v[28:31]
	v_mfma_f32_16x16x32_bf16 v[24:27], v[156:159], v[208:211], v[24:27]
	v_mfma_f32_16x16x32_bf16 v[12:15], v[134:137], v[216:219], v[12:15]
	v_mfma_f32_16x16x32_bf16 v[8:11], v[156:159], v[216:219], v[8:11]
	s_setprio 0
	s_setprio 1
	v_mfma_f32_16x16x32_bf16 v[52:55], v[160:163], v[182:185], v[52:55]
	v_mfma_f32_16x16x32_bf16 v[48:51], v[168:171], v[182:185], v[48:51]
	v_mfma_f32_16x16x32_bf16 v[36:39], v[160:163], v[196:199], v[36:39]
	v_mfma_f32_16x16x32_bf16 v[32:35], v[168:171], v[196:199], v[32:35]
	v_mfma_f32_16x16x32_bf16 v[20:23], v[160:163], v[204:207], v[20:23]
	v_mfma_f32_16x16x32_bf16 v[16:19], v[168:171], v[204:207], v[16:19]
	v_mfma_f32_16x16x32_bf16 v[4:7], v[160:163], v[212:215], v[4:7]
	v_mfma_f32_16x16x32_bf16 v[0:3], v[168:171], v[212:215], v[0:3]
	v_mfma_f32_16x16x32_bf16 v[52:55], v[164:167], v[192:195], v[52:55]
	v_mfma_f32_16x16x32_bf16 v[48:51], v[178:181], v[192:195], v[48:51]
	v_mfma_f32_16x16x32_bf16 v[36:39], v[164:167], v[200:203], v[36:39]
	v_mfma_f32_16x16x32_bf16 v[32:35], v[178:181], v[200:203], v[32:35]
	v_mfma_f32_16x16x32_bf16 v[20:23], v[164:167], v[208:211], v[20:23]
	v_mfma_f32_16x16x32_bf16 v[16:19], v[178:181], v[208:211], v[16:19]
	v_mfma_f32_16x16x32_bf16 v[4:7], v[164:167], v[216:219], v[4:7]
	v_mfma_f32_16x16x32_bf16 v[0:3], v[178:181], v[216:219], v[0:3]
	s_setprio 0
	s_barrier
	s_add_i32 s20, 0, 0x18000
	v_add_u32_e32 v128, s20, v174
	s_add_i32 s80, 0, 0x1c000
	ds_read_b128 v[130:133], v128
	ds_read_b128 v[134:137], v128 offset:1024
	ds_read_b128 v[152:155], v128 offset:2048
	ds_read_b128 v[156:159], v128 offset:3072
	v_add_u32_e32 v128, s80, v174
	ds_read_b128 v[160:163], v128
	ds_read_b128 v[164:167], v128 offset:1024
	ds_read_b128 v[168:171], v128 offset:2048
	ds_read_b128 v[178:181], v128 offset:3072
	s_add_u32 s96, s96, 0x80000
	s_addc_u32 s97, s97, 0
	s_mov_b32 m0, s22
	ds_read_b128 v[182:185], v176 offset:32768
	ds_read_b128 v[192:195], v176 offset:33792
	ds_read_b128 v[196:199], v176 offset:34816
	ds_read_b128 v[200:203], v176 offset:35840
	ds_read_b128 v[204:207], v176 offset:36864
	ds_read_b128 v[208:211], v176 offset:37888
	ds_read_b128 v[212:215], v176 offset:38912
	ds_read_b128 v[216:219], v176 offset:39936
	global_load_lds_dwordx4 v138, s[96:97]
	s_mov_b32 m0, s84
	s_nop 0
	global_load_lds_dwordx4 v142, s[96:97]
	s_waitcnt vmcnt(8)
	s_waitcnt lgkmcnt(0)
	s_barrier
	s_setprio 1
	s_waitcnt lgkmcnt(0)
	v_mfma_f32_16x16x32_bf16 v[124:127], v[130:133], v[182:185], v[124:127]
	v_mfma_f32_16x16x32_bf16 v[120:123], v[152:155], v[182:185], v[120:123]
	v_mfma_f32_16x16x32_bf16 v[108:111], v[130:133], v[196:199], v[108:111]
	v_mfma_f32_16x16x32_bf16 v[104:107], v[152:155], v[196:199], v[104:107]
	v_mfma_f32_16x16x32_bf16 v[92:95], v[130:133], v[204:207], v[92:95]
	v_mfma_f32_16x16x32_bf16 v[88:91], v[152:155], v[204:207], v[88:91]
	v_mfma_f32_16x16x32_bf16 v[76:79], v[130:133], v[212:215], v[76:79]
	v_mfma_f32_16x16x32_bf16 v[72:75], v[152:155], v[212:215], v[72:75]
	v_mfma_f32_16x16x32_bf16 v[124:127], v[134:137], v[192:195], v[124:127]
	v_mfma_f32_16x16x32_bf16 v[120:123], v[156:159], v[192:195], v[120:123]
	v_mfma_f32_16x16x32_bf16 v[108:111], v[134:137], v[200:203], v[108:111]
	v_mfma_f32_16x16x32_bf16 v[104:107], v[156:159], v[200:203], v[104:107]
	v_mfma_f32_16x16x32_bf16 v[92:95], v[134:137], v[208:211], v[92:95]
	v_mfma_f32_16x16x32_bf16 v[88:91], v[156:159], v[208:211], v[88:91]
	v_mfma_f32_16x16x32_bf16 v[76:79], v[134:137], v[216:219], v[76:79]
	v_mfma_f32_16x16x32_bf16 v[72:75], v[156:159], v[216:219], v[72:75]
	s_setprio 0
	s_setprio 1
	v_mfma_f32_16x16x32_bf16 v[116:119], v[160:163], v[182:185], v[116:119]
	v_mfma_f32_16x16x32_bf16 v[112:115], v[168:171], v[182:185], v[112:115]
	v_mfma_f32_16x16x32_bf16 v[100:103], v[160:163], v[196:199], v[100:103]
	v_mfma_f32_16x16x32_bf16 v[96:99], v[168:171], v[196:199], v[96:99]
	v_mfma_f32_16x16x32_bf16 v[84:87], v[160:163], v[204:207], v[84:87]
	v_mfma_f32_16x16x32_bf16 v[80:83], v[168:171], v[204:207], v[80:83]
	v_mfma_f32_16x16x32_bf16 v[68:71], v[160:163], v[212:215], v[68:71]
	v_mfma_f32_16x16x32_bf16 v[64:67], v[168:171], v[212:215], v[64:67]
	v_mfma_f32_16x16x32_bf16 v[116:119], v[164:167], v[192:195], v[116:119]
	v_mfma_f32_16x16x32_bf16 v[112:115], v[178:181], v[192:195], v[112:115]
	v_mfma_f32_16x16x32_bf16 v[100:103], v[164:167], v[200:203], v[100:103]
	v_mfma_f32_16x16x32_bf16 v[96:99], v[178:181], v[200:203], v[96:99]
	v_mfma_f32_16x16x32_bf16 v[84:87], v[164:167], v[208:211], v[84:87]
	v_mfma_f32_16x16x32_bf16 v[80:83], v[178:181], v[208:211], v[80:83]
	v_mfma_f32_16x16x32_bf16 v[68:71], v[164:167], v[216:219], v[68:71]
	v_mfma_f32_16x16x32_bf16 v[64:67], v[178:181], v[216:219], v[64:67]
	s_setprio 0
	s_barrier
	s_add_i32 s20, s20, s33
	v_lshl_add_u64 v[220:221], v[220:221], 0, s[92:93]
	s_mov_b32 m0, s20
	ds_read_b128 v[182:185], v176 offset:49152
	ds_read_b128 v[192:195], v176 offset:50176
	ds_read_b128 v[196:199], v176 offset:51200
	ds_read_b128 v[200:203], v176 offset:52224
	ds_read_b128 v[204:207], v176 offset:53248
	ds_read_b128 v[208:211], v176 offset:54272
	ds_read_b128 v[212:215], v176 offset:55296
	ds_read_b128 v[216:219], v176 offset:56320
	global_load_lds_dwordx4 v[220:221], off
	s_add_i32 m0, s20, 0x2000
	s_add_u32 s66, s66, 0x80080
	v_lshl_add_u64 v[220:221], v[222:223], 0, s[92:93]
	s_addc_u32 s67, s67, 0
	s_add_i32 s20, s80, s33
	global_load_lds_dwordx4 v[220:221], off
	s_mov_b32 m0, s20
	s_nop 0
	global_load_lds_dwordx4 v140, s[66:67]
	s_add_i32 m0, s20, 0x2000
	s_nop 0
	global_load_lds_dwordx4 v144, s[66:67]
	v_lshl_add_u64 v[220:221], v[224:225], 0, s[92:93]
	s_mov_b32 m0, s45
	s_nop 0
	global_load_lds_dwordx4 v[220:221], off
	v_lshl_add_u64 v[220:221], v[226:227], 0, s[92:93]
	s_mov_b32 m0, s16
	s_nop 0
	global_load_lds_dwordx4 v[220:221], off
	s_waitcnt vmcnt(8)
	s_waitcnt lgkmcnt(0)
	s_barrier
	s_setprio 1
	s_waitcnt lgkmcnt(0)
	v_mfma_f32_16x16x32_bf16 v[60:63], v[130:133], v[182:185], v[60:63]
	v_mfma_f32_16x16x32_bf16 v[56:59], v[152:155], v[182:185], v[56:59]
	v_mfma_f32_16x16x32_bf16 v[44:47], v[130:133], v[196:199], v[44:47]
	v_mfma_f32_16x16x32_bf16 v[40:43], v[152:155], v[196:199], v[40:43]
	v_mfma_f32_16x16x32_bf16 v[28:31], v[130:133], v[204:207], v[28:31]
	v_mfma_f32_16x16x32_bf16 v[24:27], v[152:155], v[204:207], v[24:27]
	v_mfma_f32_16x16x32_bf16 v[12:15], v[130:133], v[212:215], v[12:15]
	v_mfma_f32_16x16x32_bf16 v[8:11], v[152:155], v[212:215], v[8:11]
	v_mfma_f32_16x16x32_bf16 v[60:63], v[134:137], v[192:195], v[60:63]
	v_mfma_f32_16x16x32_bf16 v[56:59], v[156:159], v[192:195], v[56:59]
	v_mfma_f32_16x16x32_bf16 v[44:47], v[134:137], v[200:203], v[44:47]
	v_mfma_f32_16x16x32_bf16 v[40:43], v[156:159], v[200:203], v[40:43]
	v_mfma_f32_16x16x32_bf16 v[28:31], v[134:137], v[208:211], v[28:31]
	v_mfma_f32_16x16x32_bf16 v[24:27], v[156:159], v[208:211], v[24:27]
	v_mfma_f32_16x16x32_bf16 v[12:15], v[134:137], v[216:219], v[12:15]
	v_mfma_f32_16x16x32_bf16 v[8:11], v[156:159], v[216:219], v[8:11]
	s_setprio 0
	s_setprio 1
	v_mfma_f32_16x16x32_bf16 v[52:55], v[160:163], v[182:185], v[52:55]
	v_mfma_f32_16x16x32_bf16 v[48:51], v[168:171], v[182:185], v[48:51]
	v_mfma_f32_16x16x32_bf16 v[36:39], v[160:163], v[196:199], v[36:39]
	v_mfma_f32_16x16x32_bf16 v[32:35], v[168:171], v[196:199], v[32:35]
	v_mfma_f32_16x16x32_bf16 v[20:23], v[160:163], v[204:207], v[20:23]
	v_mfma_f32_16x16x32_bf16 v[16:19], v[168:171], v[204:207], v[16:19]
	v_mfma_f32_16x16x32_bf16 v[4:7], v[160:163], v[212:215], v[4:7]
	v_mfma_f32_16x16x32_bf16 v[0:3], v[168:171], v[212:215], v[0:3]
	v_mfma_f32_16x16x32_bf16 v[52:55], v[164:167], v[192:195], v[52:55]
	v_mfma_f32_16x16x32_bf16 v[48:51], v[178:181], v[192:195], v[48:51]
	v_mfma_f32_16x16x32_bf16 v[36:39], v[164:167], v[200:203], v[36:39]
	v_mfma_f32_16x16x32_bf16 v[32:35], v[178:181], v[200:203], v[32:35]
	v_mfma_f32_16x16x32_bf16 v[20:23], v[164:167], v[208:211], v[20:23]
	v_mfma_f32_16x16x32_bf16 v[16:19], v[178:181], v[208:211], v[16:19]
	v_mfma_f32_16x16x32_bf16 v[4:7], v[164:167], v[216:219], v[4:7]
	v_mfma_f32_16x16x32_bf16 v[0:3], v[178:181], v[216:219], v[0:3]
	s_setprio 0
	s_barrier
	s_add_i32 s90, s90, 2
	s_add_u32 s0, s0, 0x100
	s_addc_u32 s1, s1, 0
	s_add_u32 s59, s59, 0x100
	s_addc_u32 s61, s61, 0
	s_cmp_gt_u32 s90, 29
	s_cbranch_scc0 .LBB0_114
	s_and_b64 vcc, exec, s[56:57]
	s_cbranch_vccz .LBB0_117
	s_barrier

.LBB0_232:
	s_add_u32 s8, s6, 0xfff80080
	s_addc_u32 s9, s7, -1
	s_add_i32 s80, 0, 0x10000
	s_cmp_eq_u32 s20, 28
	s_cselect_b32 s11, s67, s9
	s_cselect_b32 s10, s96, s8
	s_cselect_b32 s9, s65, vcc_hi
	s_cselect_b32 s8, s97, vcc_lo
	s_add_i32 s34, 0, 0x14000
	v_add_u32_e32 v76, s80, v215
	v_add_u32_e32 v158, s34, v215
	ds_read_b128 v[64:67], v76
	ds_read_b128 v[68:71], v76 offset:1024
	ds_read_b128 v[72:75], v76 offset:2048
	ds_read_b128 v[76:79], v76 offset:3072
	ds_read_b128 v[146:149], v158
	ds_read_b128 v[150:153], v158 offset:1024
	ds_read_b128 v[154:157], v158 offset:2048
	ds_read_b128 v[158:161], v158 offset:3072
	s_add_i32 m0, s22, 0xc000
	ds_read_b128 v[162:165], v217
	ds_read_b128 v[166:169], v217 offset:1024
	ds_read_b128 v[170:173], v217 offset:2048
	ds_read_b128 v[174:177], v217 offset:3072
	ds_read_b128 v[194:197], v217 offset:4096
	ds_read_b128 v[198:201], v217 offset:5120
	ds_read_b128 v[202:205], v217 offset:6144
	ds_read_b128 v[206:209], v217 offset:7168
	global_load_lds_dwordx4 v184, s[6:7]
	s_add_i32 m0, s22, 0xe000
	s_nop 0
	global_load_lds_dwordx4 v192, s[6:7]
	s_waitcnt vmcnt(8)
	s_waitcnt lgkmcnt(0)
	s_barrier
	s_setprio 1
	s_waitcnt lgkmcnt(0)
	v_mfma_f32_16x16x32_bf16 v[142:145], v[64:67], v[162:165], v[142:145]
	v_mfma_f32_16x16x32_bf16 v[138:141], v[72:75], v[162:165], v[138:141]
	v_mfma_f32_16x16x32_bf16 v[124:127], v[64:67], v[170:173], v[124:127]
	v_mfma_f32_16x16x32_bf16 v[120:123], v[72:75], v[170:173], v[120:123]
	v_mfma_f32_16x16x32_bf16 v[108:111], v[64:67], v[194:197], v[108:111]
	v_mfma_f32_16x16x32_bf16 v[104:107], v[72:75], v[194:197], v[104:107]
	v_mfma_f32_16x16x32_bf16 v[92:95], v[64:67], v[202:205], v[92:95]
	v_mfma_f32_16x16x32_bf16 v[88:91], v[72:75], v[202:205], v[88:91]
	v_mfma_f32_16x16x32_bf16 v[142:145], v[68:71], v[166:169], v[142:145]
	v_mfma_f32_16x16x32_bf16 v[138:141], v[76:79], v[166:169], v[138:141]
	v_mfma_f32_16x16x32_bf16 v[124:127], v[68:71], v[174:177], v[124:127]
	v_mfma_f32_16x16x32_bf16 v[120:123], v[76:79], v[174:177], v[120:123]
	v_mfma_f32_16x16x32_bf16 v[108:111], v[68:71], v[198:201], v[108:111]
	v_mfma_f32_16x16x32_bf16 v[104:107], v[76:79], v[198:201], v[104:107]
	v_mfma_f32_16x16x32_bf16 v[92:95], v[68:71], v[206:209], v[92:95]
	v_mfma_f32_16x16x32_bf16 v[88:91], v[76:79], v[206:209], v[88:91]
	s_setprio 0
	s_setprio 1
	v_mfma_f32_16x16x32_bf16 v[134:137], v[146:149], v[162:165], v[134:137]
	v_mfma_f32_16x16x32_bf16 v[130:133], v[154:157], v[162:165], v[130:133]
	v_mfma_f32_16x16x32_bf16 v[116:119], v[146:149], v[170:173], v[116:119]
	v_mfma_f32_16x16x32_bf16 v[112:115], v[154:157], v[170:173], v[112:115]
	v_mfma_f32_16x16x32_bf16 v[100:103], v[146:149], v[194:197], v[100:103]
	v_mfma_f32_16x16x32_bf16 v[96:99], v[154:157], v[194:197], v[96:99]
	v_mfma_f32_16x16x32_bf16 v[84:87], v[146:149], v[202:205], v[84:87]
	v_mfma_f32_16x16x32_bf16 v[80:83], v[154:157], v[202:205], v[80:83]
	v_mfma_f32_16x16x32_bf16 v[134:137], v[150:153], v[166:169], v[134:137]
	v_mfma_f32_16x16x32_bf16 v[130:133], v[158:161], v[166:169], v[130:133]
	v_mfma_f32_16x16x32_bf16 v[116:119], v[150:153], v[174:177], v[116:119]
	v_mfma_f32_16x16x32_bf16 v[112:115], v[158:161], v[174:177], v[112:115]
	v_mfma_f32_16x16x32_bf16 v[100:103], v[150:153], v[198:201], v[100:103]
	v_mfma_f32_16x16x32_bf16 v[96:99], v[158:161], v[198:201], v[96:99]
	v_mfma_f32_16x16x32_bf16 v[84:87], v[150:153], v[206:209], v[84:87]
	v_mfma_f32_16x16x32_bf16 v[80:83], v[158:161], v[206:209], v[80:83]
	s_setprio 0
	s_barrier
	s_add_i32 s35, s80, s21
	v_lshl_add_u64 v[186:187], s[8:9], 0, v[128:129]
	s_mov_b32 m0, s35
	ds_read_b128 v[162:165], v217 offset:16384
	ds_read_b128 v[166:169], v217 offset:17408
	ds_read_b128 v[170:173], v217 offset:18432
	ds_read_b128 v[174:177], v217 offset:19456
	ds_read_b128 v[194:197], v217 offset:20480
	ds_read_b128 v[198:201], v217 offset:21504
	ds_read_b128 v[202:205], v217 offset:22528
	ds_read_b128 v[206:209], v217 offset:23552
	global_load_lds_dwordx4 v[186:187], off
	s_add_i32 m0, s35, 0x2000
	s_add_u32 s80, s8, 0x80000
	v_lshl_add_u64 v[190:191], s[8:9], 0, v[178:179]
	s_addc_u32 s81, s9, 0
	s_add_i32 s34, s34, s21
	global_load_lds_dwordx4 v[190:191], off
	s_mov_b32 m0, s34
	v_lshl_add_u64 v[212:213], s[10:11], 0, v[180:181]
	global_load_lds_dwordx4 v128, s[80:81]
	s_add_i32 m0, s34, 0x2000
	s_nop 0
	global_load_lds_dwordx4 v178, s[80:81]
	v_lshl_add_u64 v[210:211], s[10:11], 0, v[182:183]
	s_mov_b32 m0, s22
	s_nop 0
	global_load_lds_dwordx4 v[210:211], off
	s_mov_b32 m0, s23
	s_nop 0
	global_load_lds_dwordx4 v[212:213], off
	s_waitcnt vmcnt(8)
	s_waitcnt lgkmcnt(0)
	s_barrier
	s_setprio 1
	s_waitcnt lgkmcnt(0)
	v_mfma_f32_16x16x32_bf16 v[60:63], v[64:67], v[162:165], v[60:63]
	v_mfma_f32_16x16x32_bf16 v[56:59], v[72:75], v[162:165], v[56:59]
	v_mfma_f32_16x16x32_bf16 v[44:47], v[64:67], v[170:173], v[44:47]
	v_mfma_f32_16x16x32_bf16 v[40:43], v[72:75], v[170:173], v[40:43]
	v_mfma_f32_16x16x32_bf16 v[28:31], v[64:67], v[194:197], v[28:31]
	v_mfma_f32_16x16x32_bf16 v[24:27], v[72:75], v[194:197], v[24:27]
	v_mfma_f32_16x16x32_bf16 v[12:15], v[64:67], v[202:205], v[12:15]
	v_mfma_f32_16x16x32_bf16 v[8:11], v[72:75], v[202:205], v[8:11]
	v_mfma_f32_16x16x32_bf16 v[60:63], v[68:71], v[166:169], v[60:63]
	v_mfma_f32_16x16x32_bf16 v[56:59], v[76:79], v[166:169], v[56:59]
	v_mfma_f32_16x16x32_bf16 v[44:47], v[68:71], v[174:177], v[44:47]
	v_mfma_f32_16x16x32_bf16 v[40:43], v[76:79], v[174:177], v[40:43]
	v_mfma_f32_16x16x32_bf16 v[28:31], v[68:71], v[198:201], v[28:31]
	v_mfma_f32_16x16x32_bf16 v[24:27], v[76:79], v[198:201], v[24:27]
	v_mfma_f32_16x16x32_bf16 v[12:15], v[68:71], v[206:209], v[12:15]
	v_mfma_f32_16x16x32_bf16 v[8:11], v[76:79], v[206:209], v[8:11]
	s_setprio 0
	s_setprio 1
	v_mfma_f32_16x16x32_bf16 v[52:55], v[146:149], v[162:165], v[52:55]
	v_mfma_f32_16x16x32_bf16 v[48:51], v[154:157], v[162:165], v[48:51]
	v_mfma_f32_16x16x32_bf16 v[36:39], v[146:149], v[170:173], v[36:39]
	v_mfma_f32_16x16x32_bf16 v[32:35], v[154:157], v[170:173], v[32:35]
	v_mfma_f32_16x16x32_bf16 v[20:23], v[146:149], v[194:197], v[20:23]
	v_mfma_f32_16x16x32_bf16 v[16:19], v[154:157], v[194:197], v[16:19]
	v_mfma_f32_16x16x32_bf16 v[4:7], v[146:149], v[202:205], v[4:7]
	v_mfma_f32_16x16x32_bf16 v[0:3], v[154:157], v[202:205], v[0:3]
	v_mfma_f32_16x16x32_bf16 v[52:55], v[150:153], v[166:169], v[52:55]
	v_mfma_f32_16x16x32_bf16 v[48:51], v[158:161], v[166:169], v[48:51]
	v_mfma_f32_16x16x32_bf16 v[36:39], v[150:153], v[174:177], v[36:39]
	v_mfma_f32_16x16x32_bf16 v[32:35], v[158:161], v[174:177], v[32:35]
	v_mfma_f32_16x16x32_bf16 v[20:23], v[150:153], v[198:201], v[20:23]
	v_mfma_f32_16x16x32_bf16 v[16:19], v[158:161], v[198:201], v[16:19]
	v_mfma_f32_16x16x32_bf16 v[4:7], v[150:153], v[206:209], v[4:7]
	v_mfma_f32_16x16x32_bf16 v[0:3], v[158:161], v[206:209], v[0:3]
	s_setprio 0
	s_barrier
	s_add_i32 s34, 0, 0x18000
	s_add_i32 s35, 0, 0x1c000
	v_add_u32_e32 v76, s34, v215
	v_add_u32_e32 v158, s35, v215
	ds_read_b128 v[64:67], v76
	ds_read_b128 v[68:71], v76 offset:1024
	ds_read_b128 v[72:75], v76 offset:2048
	ds_read_b128 v[76:79], v76 offset:3072
	ds_read_b128 v[146:149], v158
	ds_read_b128 v[150:153], v158 offset:1024
	ds_read_b128 v[154:157], v158 offset:2048
	ds_read_b128 v[158:161], v158 offset:3072
	s_add_u32 s10, s10, 0x80000
	s_addc_u32 s11, s11, 0
	s_mov_b32 m0, s33
	ds_read_b128 v[162:165], v217 offset:32768
	ds_read_b128 v[166:169], v217 offset:33792
	ds_read_b128 v[170:173], v217 offset:34816
	ds_read_b128 v[174:177], v217 offset:35840
	ds_read_b128 v[194:197], v217 offset:36864
	ds_read_b128 v[198:201], v217 offset:37888
	ds_read_b128 v[202:205], v217 offset:38912
	ds_read_b128 v[206:209], v217 offset:39936
	global_load_lds_dwordx4 v182, s[10:11]
	s_mov_b32 m0, s44
	s_nop 0
	global_load_lds_dwordx4 v180, s[10:11]
	s_waitcnt vmcnt(8)
	s_waitcnt lgkmcnt(0)
	s_barrier
	s_setprio 1
	s_waitcnt lgkmcnt(0)
	v_mfma_f32_16x16x32_bf16 v[142:145], v[64:67], v[162:165], v[142:145]
	v_mfma_f32_16x16x32_bf16 v[138:141], v[72:75], v[162:165], v[138:141]
	v_mfma_f32_16x16x32_bf16 v[124:127], v[64:67], v[170:173], v[124:127]
	v_mfma_f32_16x16x32_bf16 v[120:123], v[72:75], v[170:173], v[120:123]
	v_mfma_f32_16x16x32_bf16 v[108:111], v[64:67], v[194:197], v[108:111]
	v_mfma_f32_16x16x32_bf16 v[104:107], v[72:75], v[194:197], v[104:107]
	v_mfma_f32_16x16x32_bf16 v[92:95], v[64:67], v[202:205], v[92:95]
	v_mfma_f32_16x16x32_bf16 v[88:91], v[72:75], v[202:205], v[88:91]
	v_mfma_f32_16x16x32_bf16 v[142:145], v[68:71], v[166:169], v[142:145]
	v_mfma_f32_16x16x32_bf16 v[138:141], v[76:79], v[166:169], v[138:141]
	v_mfma_f32_16x16x32_bf16 v[124:127], v[68:71], v[174:177], v[124:127]
	v_mfma_f32_16x16x32_bf16 v[120:123], v[76:79], v[174:177], v[120:123]
	v_mfma_f32_16x16x32_bf16 v[108:111], v[68:71], v[198:201], v[108:111]
	v_mfma_f32_16x16x32_bf16 v[104:107], v[76:79], v[198:201], v[104:107]
	v_mfma_f32_16x16x32_bf16 v[92:95], v[68:71], v[206:209], v[92:95]
	v_mfma_f32_16x16x32_bf16 v[88:91], v[76:79], v[206:209], v[88:91]
	s_setprio 0
	s_setprio 1
	v_mfma_f32_16x16x32_bf16 v[134:137], v[146:149], v[162:165], v[134:137]
	v_mfma_f32_16x16x32_bf16 v[130:133], v[154:157], v[162:165], v[130:133]
	v_mfma_f32_16x16x32_bf16 v[116:119], v[146:149], v[170:173], v[116:119]
	v_mfma_f32_16x16x32_bf16 v[112:115], v[154:157], v[170:173], v[112:115]
	v_mfma_f32_16x16x32_bf16 v[100:103], v[146:149], v[194:197], v[100:103]
	v_mfma_f32_16x16x32_bf16 v[96:99], v[154:157], v[194:197], v[96:99]
	v_mfma_f32_16x16x32_bf16 v[84:87], v[146:149], v[202:205], v[84:87]
	v_mfma_f32_16x16x32_bf16 v[80:83], v[154:157], v[202:205], v[80:83]
	v_mfma_f32_16x16x32_bf16 v[134:137], v[150:153], v[166:169], v[134:137]
	v_mfma_f32_16x16x32_bf16 v[130:133], v[158:161], v[166:169], v[130:133]
	v_mfma_f32_16x16x32_bf16 v[116:119], v[150:153], v[174:177], v[116:119]
	v_mfma_f32_16x16x32_bf16 v[112:115], v[158:161], v[174:177], v[112:115]
	v_mfma_f32_16x16x32_bf16 v[100:103], v[150:153], v[198:201], v[100:103]
	v_mfma_f32_16x16x32_bf16 v[96:99], v[158:161], v[198:201], v[96:99]
	v_mfma_f32_16x16x32_bf16 v[84:87], v[150:153], v[206:209], v[84:87]
	v_mfma_f32_16x16x32_bf16 v[80:83], v[158:161], v[206:209], v[80:83]
	s_setprio 0
	s_barrier
	s_add_i32 s10, s34, s21
	v_lshl_add_u64 v[186:187], v[186:187], 0, s[92:93]
	s_mov_b32 m0, s10
	ds_read_b128 v[162:165], v217 offset:49152
	ds_read_b128 v[166:169], v217 offset:50176
	ds_read_b128 v[170:173], v217 offset:51200
	ds_read_b128 v[174:177], v217 offset:52224
	ds_read_b128 v[194:197], v217 offset:53248
	ds_read_b128 v[198:201], v217 offset:54272
	ds_read_b128 v[202:205], v217 offset:55296
	ds_read_b128 v[206:209], v217 offset:56320
	global_load_lds_dwordx4 v[186:187], off
	s_add_i32 m0, s10, 0x2000
	s_add_u32 s8, s8, 0x80080
	v_lshl_add_u64 v[186:187], v[190:191], 0, s[92:93]
	s_addc_u32 s9, s9, 0
	s_add_i32 s10, s35, s21
	global_load_lds_dwordx4 v[186:187], off
	s_mov_b32 m0, s10
	s_nop 0
	global_load_lds_dwordx4 v128, s[8:9]
	s_add_i32 m0, s10, 0x2000
	s_nop 0
	global_load_lds_dwordx4 v178, s[8:9]
	v_lshl_add_u64 v[186:187], v[210:211], 0, s[92:93]
	s_mov_b32 m0, s1
	s_nop 0
	global_load_lds_dwordx4 v[186:187], off
	v_lshl_add_u64 v[186:187], v[212:213], 0, s[92:93]
	s_mov_b32 m0, s3
	s_nop 0
	global_load_lds_dwordx4 v[186:187], off
	s_waitcnt vmcnt(8)
	s_waitcnt lgkmcnt(0)
	s_barrier
	s_setprio 1
	s_waitcnt lgkmcnt(0)
	v_mfma_f32_16x16x32_bf16 v[60:63], v[64:67], v[162:165], v[60:63]
	v_mfma_f32_16x16x32_bf16 v[56:59], v[72:75], v[162:165], v[56:59]
	v_mfma_f32_16x16x32_bf16 v[44:47], v[64:67], v[170:173], v[44:47]
	v_mfma_f32_16x16x32_bf16 v[40:43], v[72:75], v[170:173], v[40:43]
	v_mfma_f32_16x16x32_bf16 v[28:31], v[64:67], v[194:197], v[28:31]
	v_mfma_f32_16x16x32_bf16 v[24:27], v[72:75], v[194:197], v[24:27]
	v_mfma_f32_16x16x32_bf16 v[12:15], v[64:67], v[202:205], v[12:15]
	v_mfma_f32_16x16x32_bf16 v[8:11], v[72:75], v[202:205], v[8:11]
	v_mfma_f32_16x16x32_bf16 v[60:63], v[68:71], v[166:169], v[60:63]
	v_mfma_f32_16x16x32_bf16 v[56:59], v[76:79], v[166:169], v[56:59]
	v_mfma_f32_16x16x32_bf16 v[44:47], v[68:71], v[174:177], v[44:47]
	v_mfma_f32_16x16x32_bf16 v[40:43], v[76:79], v[174:177], v[40:43]
	v_mfma_f32_16x16x32_bf16 v[28:31], v[68:71], v[198:201], v[28:31]
	v_mfma_f32_16x16x32_bf16 v[24:27], v[76:79], v[198:201], v[24:27]
	v_mfma_f32_16x16x32_bf16 v[12:15], v[68:71], v[206:209], v[12:15]
	v_mfma_f32_16x16x32_bf16 v[8:11], v[76:79], v[206:209], v[8:11]
	s_setprio 0
	s_setprio 1
	v_mfma_f32_16x16x32_bf16 v[52:55], v[146:149], v[162:165], v[52:55]
	v_mfma_f32_16x16x32_bf16 v[48:51], v[154:157], v[162:165], v[48:51]
	v_mfma_f32_16x16x32_bf16 v[36:39], v[146:149], v[170:173], v[36:39]
	v_mfma_f32_16x16x32_bf16 v[32:35], v[154:157], v[170:173], v[32:35]
	v_mfma_f32_16x16x32_bf16 v[20:23], v[146:149], v[194:197], v[20:23]
	v_mfma_f32_16x16x32_bf16 v[16:19], v[154:157], v[194:197], v[16:19]
	v_mfma_f32_16x16x32_bf16 v[4:7], v[146:149], v[202:205], v[4:7]
	v_mfma_f32_16x16x32_bf16 v[0:3], v[154:157], v[202:205], v[0:3]
	v_mfma_f32_16x16x32_bf16 v[52:55], v[150:153], v[166:169], v[52:55]
	v_mfma_f32_16x16x32_bf16 v[48:51], v[158:161], v[166:169], v[48:51]
	v_mfma_f32_16x16x32_bf16 v[36:39], v[150:153], v[174:177], v[36:39]
	v_mfma_f32_16x16x32_bf16 v[32:35], v[158:161], v[174:177], v[32:35]
	v_mfma_f32_16x16x32_bf16 v[20:23], v[150:153], v[198:201], v[20:23]
	v_mfma_f32_16x16x32_bf16 v[16:19], v[158:161], v[198:201], v[16:19]
	v_mfma_f32_16x16x32_bf16 v[4:7], v[150:153], v[206:209], v[4:7]
	v_mfma_f32_16x16x32_bf16 v[0:3], v[158:161], v[206:209], v[0:3]
	s_setprio 0
	s_barrier
	s_add_i32 s20, s20, 2
	s_add_u32 s6, s6, 0x100
	s_addc_u32 s7, s7, 0
	s_add_u32 vcc_lo, vcc_lo, 0x100
	s_addc_u32 vcc_hi, vcc_hi, 0
	s_cmp_gt_u32 s20, 29
	s_cbranch_scc0 .LBB0_232
	s_and_b64 vcc, exec, s[60:61]
	s_cbranch_vccz .LBB0_235
	s_barrier
